# nb8: grid barrier 8 removed - piece waves signal a per-XCD counter, the 128 non-piece workgroups elect one L2 flusher per XCD, wait for all 8, and run P8 (final norm of sample rows) while the piece wo
# baseline (speedup 1.0000x reference)
;     __host__ __device__ void init(int M, int N, int K, int G_, int c_, int tailM_, int nsplit_) { so.init(M, N, K, G_, c_); tailM = tailM_; nsplit = nsplit_; npieces = tailM_ * so.nN * nsplit_; }
; __global__ void __launch_bounds__(512, 2) fwd_megakernel(Params P) {
;     ...
;     {
;         pg8::Gemm g{(const bf16_t*)(ws + WS_U), (const bf16_t*)(ws + WS_WDN), MT, DM, FF}; pg8::TailSplitOrder S; S.init(MP, DM, FF, G, bx, MS / 256, NSPLIT_DN);
;         pg8::EpiDownNorm E{(const bf16_t*)(ws + WS_H1B), P.out + O_Y, (bf16_t*)(ws + WS_SLAB), P.norm_f, (float*)(ws + WS_XBUF), (unsigned*)(ws + WS_CNT)};
;         pg8::gemm_phase<pg8::EpiDownNorm, pg8::TailSplitOrder, true, true>(lds, g, S, E, wave0);
;     }
;     xcd_barrier(bar);
;     { FRESH_IDS; final_norm(P, G, wave, lane, P.out + O_Y); }
.Lsp7_h:
	s_cmp_eq_u32 s101, 0x8888
	s_cbranch_scc1 .Lnb8_h
	s_cmp_eq_u32 s73, 4
	s_cbranch_scc0 .Lsp7_h2
	s_mov_b64 exec, 1
	s_lshl_b32 s98, s33, 8
	s_add_u32 s98, s98, 0x82400
	v_mov_b32_e32 v246, s98
	global_load_dword v247, v246, s[68:69] sc1
	s_mov_b64 exec, -1
	s_branch .Lsp7_back

; __global__ void __launch_bounds__(512, 2) fwd_megakernel(Params P) {
;     ...
;     xcd_barrier(bar);
;     { FRESH_IDS; final_norm(P, G, wave, lane, P.out + O_Y); }
.Lnb8_h:
	s_cmp_eq_u32 s73, 8
	s_cbranch_scc0 .Lsp7_back
	s_mov_b64 exec, 1
	s_lshl_b32 s98, s33, 8
	s_add_u32 s98, s98, 0x54000
	v_mov_b32_e32 v246, s98
	v_mov_b32_e32 v247, 1
	global_atomic_add v246, v247, s[68:69]
	s_mov_b32 s99, 0
	s_mov_b32 s101, 0
	s_mov_b64 exec, -1
	s_branch .Lsp7_back

;     __device__ __forceinline__ void operator()(f32x4 (&acc)[2][2][4][2], const Unit& u, int wr, int wc, int fr, int fq) const {
; #pragma unroll
;         for (int ai = 0; ai < 2; ++ai)
; #pragma unroll
;             for (int m = 0; m < 4; ++m) {
;                 const int r = u.pm * BM + ai * HALF + wr * 64 + m * 16 + fr;
; #pragma unroll
;                 for (int bj = 0; bj < 2; ++bj)
;                     st8bf(slab + (size_t)(u.k0 / u.nt) * ((size_t)MS * DM) + (size_t)(r - MP) * DM + u.pn * BM + wc * 64 + bj * 32 + 8 * fq, acc[ai][bj][m][0], acc[ai][bj][m][1]);
;             }
;     }
.LBB0_1057:
	s_andn2_b64 vcc, exec, s[40:41]
	s_cbranch_vccnz .LBB0_1046
	s_cmp_lg_u32 s100, 0
	s_cbranch_scc1 .Lnb8_ps
	s_mov_b32 s99, 0x7777
	s_mov_b32 s101, 0x8888
.Lnb8_ps:
	s_abs_i32 s11, s57
	v_cvt_f32_u32_e32 v128, s11
	s_sub_i32 s13, 0, s11
	s_lshl_b32 s23, s12, 8
	s_xor_b32 s12, s0, s57
	v_rcp_iflag_f32_e32 v128, v128
	s_abs_i32 s0, s0
	s_ashr_i32 s12, s12, 31
	v_add_u32_e32 v130, s23, v162
	v_mul_f32_e32 v128, 0x4f7ffffe, v128
	v_cvt_u32_f32_e32 v128, v128
	v_cvt_pk_bf16_f32 v116, v116, v117
	v_cvt_pk_bf16_f32 v117, v118, v119
	v_cvt_pk_bf16_f32 v118, v112, v113
	v_readfirstlane_b32 s25, v128
	s_mul_i32 s13, s13, s25
	s_mul_hi_u32 s13, s25, s13
	s_add_i32 s25, s25, s13
	s_mul_hi_u32 s13, s0, s25
	s_mul_i32 s25, s13, s11
	s_sub_i32 s0, s0, s25
	s_add_i32 s27, s13, 1
	s_sub_i32 s25, s0, s11
	s_cmp_ge_u32 s0, s11
	s_cselect_b32 s13, s27, s13
	s_cselect_b32 s0, s25, s0
	s_add_i32 s25, s13, 1
	s_cmp_ge_u32 s0, s11
	s_cselect_b32 s0, s25, s13
	s_xor_b32 s0, s0, s12
	s_sub_i32 s12, s0, s12
	s_ashr_i32 s13, s12, 31
	s_lshl_b64 s[12:13], s[12:13], 21
	s_add_u32 s12, s6, s12
	v_add_u32_e32 v112, s23, v161
	v_cvt_pk_bf16_f32 v100, v100, v101
	v_cvt_pk_bf16_f32 v101, v102, v103
	v_cvt_pk_bf16_f32 v102, v96, v97
	v_add_u32_e32 v96, s23, v160
	v_cvt_pk_bf16_f32 v84, v84, v85
	v_cvt_pk_bf16_f32 v85, v86, v87
	v_cvt_pk_bf16_f32 v86, v80, v81
	v_add_u32_e32 v80, s23, v159
	v_cvt_pk_bf16_f32 v68, v68, v69
	v_cvt_pk_bf16_f32 v69, v70, v71
	v_cvt_pk_bf16_f32 v70, v64, v65
	v_add_u32_e32 v64, s23, v158
	v_cvt_pk_bf16_f32 v52, v52, v53
	v_cvt_pk_bf16_f32 v53, v54, v55
	v_cvt_pk_bf16_f32 v54, v48, v49
	v_add_u32_e32 v48, s23, v157
	v_cvt_pk_bf16_f32 v36, v36, v37
	v_cvt_pk_bf16_f32 v37, v38, v39
	v_cvt_pk_bf16_f32 v38, v32, v33
	v_add_u32_e32 v32, s23, v156
	v_cvt_pk_bf16_f32 v20, v20, v21
	v_cvt_pk_bf16_f32 v21, v22, v23
	v_cvt_pk_bf16_f32 v22, v16, v17
	v_add_u32_e32 v16, s23, v155
	v_ashrrev_i32_e32 v131, 31, v130
	s_addc_u32 s13, s7, s13
	s_lshl_b32 s10, s10, 8
	v_ashrrev_i32_e32 v113, 31, v112
	v_ashrrev_i32_e32 v97, 31, v96
	v_ashrrev_i32_e32 v81, 31, v80
	v_ashrrev_i32_e32 v65, 31, v64
	v_ashrrev_i32_e32 v49, 31, v48
	v_ashrrev_i32_e32 v33, 31, v32
	v_ashrrev_i32_e32 v17, 31, v16
	v_lshlrev_b64 v[130:131], 11, v[130:131]
	s_ashr_i32 s11, s10, 31
	v_lshlrev_b64 v[112:113], 11, v[112:113]
	v_lshlrev_b64 v[96:97], 11, v[96:97]
	v_lshlrev_b64 v[80:81], 11, v[80:81]
	v_lshlrev_b64 v[64:65], 11, v[64:65]
	v_lshlrev_b64 v[48:49], 11, v[48:49]
	v_lshlrev_b64 v[32:33], 11, v[32:33]
	v_lshlrev_b64 v[16:17], 11, v[16:17]
	v_lshl_add_u64 v[130:131], s[12:13], 0, v[130:131]
	s_lshl_b64 s[10:11], s[10:11], 1
	v_lshl_add_u64 v[112:113], s[12:13], 0, v[112:113]
	v_lshl_add_u64 v[96:97], s[12:13], 0, v[96:97]
	v_lshl_add_u64 v[80:81], s[12:13], 0, v[80:81]
	v_lshl_add_u64 v[64:65], s[12:13], 0, v[64:65]
	v_lshl_add_u64 v[48:49], s[12:13], 0, v[48:49]
	v_lshl_add_u64 v[32:33], s[12:13], 0, v[32:33]
	v_lshl_add_u64 v[16:17], s[12:13], 0, v[16:17]
	v_lshl_add_u64 v[130:131], v[130:131], 0, s[10:11]
	s_lshl_b32 s0, s46, 1
	v_lshl_add_u64 v[112:113], v[112:113], 0, s[10:11]
	v_lshl_add_u64 v[96:97], v[96:97], 0, s[10:11]
	v_lshl_add_u64 v[80:81], v[80:81], 0, s[10:11]
	v_lshl_add_u64 v[64:65], v[64:65], 0, s[10:11]
	v_lshl_add_u64 v[48:49], v[48:49], 0, s[10:11]
	v_lshl_add_u64 v[32:33], v[32:33], 0, s[10:11]
	v_lshl_add_u64 v[16:17], v[16:17], 0, s[10:11]
	v_lshl_add_u64 v[130:131], v[130:131], 0, s[0:1]
	v_lshlrev_b32_e32 v128, 1, v132
	v_lshl_add_u64 v[112:113], v[112:113], 0, s[0:1]
	v_lshl_add_u64 v[96:97], v[96:97], 0, s[0:1]
	v_lshl_add_u64 v[80:81], v[80:81], 0, s[0:1]
	v_lshl_add_u64 v[64:65], v[64:65], 0, s[0:1]
	v_lshl_add_u64 v[48:49], v[48:49], 0, s[0:1]
	v_lshl_add_u64 v[32:33], v[32:33], 0, s[0:1]
	v_lshl_add_u64 v[16:17], v[16:17], 0, s[0:1]
	v_lshl_add_u64 v[130:131], v[130:131], 0, v[128:129]
	v_cvt_pk_bf16_f32 v124, v124, v125
	v_cvt_pk_bf16_f32 v125, v126, v127
	v_cvt_pk_bf16_f32 v126, v120, v121
	v_cvt_pk_bf16_f32 v127, v122, v123
	v_cvt_pk_bf16_f32 v119, v114, v115
	v_lshl_add_u64 v[112:113], v[112:113], 0, v[128:129]
	v_cvt_pk_bf16_f32 v108, v108, v109
	v_cvt_pk_bf16_f32 v109, v110, v111
	v_cvt_pk_bf16_f32 v110, v104, v105
	v_cvt_pk_bf16_f32 v111, v106, v107
	v_cvt_pk_bf16_f32 v103, v98, v99
	v_lshl_add_u64 v[96:97], v[96:97], 0, v[128:129]
	v_cvt_pk_bf16_f32 v92, v92, v93
	v_cvt_pk_bf16_f32 v93, v94, v95
	v_cvt_pk_bf16_f32 v94, v88, v89
	v_cvt_pk_bf16_f32 v95, v90, v91
	v_cvt_pk_bf16_f32 v87, v82, v83
	v_lshl_add_u64 v[80:81], v[80:81], 0, v[128:129]
	v_cvt_pk_bf16_f32 v76, v76, v77
	v_cvt_pk_bf16_f32 v77, v78, v79
	v_cvt_pk_bf16_f32 v78, v72, v73
	v_cvt_pk_bf16_f32 v79, v74, v75
	v_cvt_pk_bf16_f32 v71, v66, v67
	v_lshl_add_u64 v[64:65], v[64:65], 0, v[128:129]
	v_cvt_pk_bf16_f32 v60, v60, v61
	v_cvt_pk_bf16_f32 v61, v62, v63
	v_cvt_pk_bf16_f32 v62, v56, v57
	v_cvt_pk_bf16_f32 v63, v58, v59
	v_cvt_pk_bf16_f32 v55, v50, v51
	v_lshl_add_u64 v[48:49], v[48:49], 0, v[128:129]
	v_cvt_pk_bf16_f32 v44, v44, v45
	v_cvt_pk_bf16_f32 v45, v46, v47
	v_cvt_pk_bf16_f32 v46, v40, v41
	v_cvt_pk_bf16_f32 v47, v42, v43
	v_cvt_pk_bf16_f32 v39, v34, v35
	v_lshl_add_u64 v[32:33], v[32:33], 0, v[128:129]
	v_cvt_pk_bf16_f32 v28, v28, v29
	v_cvt_pk_bf16_f32 v29, v30, v31
	v_cvt_pk_bf16_f32 v30, v24, v25
	v_cvt_pk_bf16_f32 v31, v26, v27
	v_cvt_pk_bf16_f32 v23, v18, v19
	v_lshl_add_u64 v[16:17], v[16:17], 0, v[128:129]
	v_cvt_pk_bf16_f32 v12, v12, v13
	v_cvt_pk_bf16_f32 v13, v14, v15
	v_cvt_pk_bf16_f32 v14, v8, v9
	v_cvt_pk_bf16_f32 v15, v10, v11
	v_cvt_pk_bf16_f32 v4, v4, v5
	v_cvt_pk_bf16_f32 v5, v6, v7
	v_cvt_pk_bf16_f32 v6, v0, v1
	v_cvt_pk_bf16_f32 v7, v2, v3
	s_andn2_b64 vcc, exec, s[14:15]
	global_store_dwordx4 v[130:131], v[124:127], off
	global_store_dwordx4 v[130:131], v[116:119], off offset:64
	global_store_dwordx4 v[112:113], v[108:111], off
	global_store_dwordx4 v[112:113], v[100:103], off offset:64
	global_store_dwordx4 v[96:97], v[92:95], off
	global_store_dwordx4 v[96:97], v[84:87], off offset:64
	global_store_dwordx4 v[80:81], v[76:79], off
	global_store_dwordx4 v[80:81], v[68:71], off offset:64
	global_store_dwordx4 v[64:65], v[60:63], off
	global_store_dwordx4 v[64:65], v[52:55], off offset:64
	global_store_dwordx4 v[48:49], v[44:47], off
	global_store_dwordx4 v[48:49], v[36:39], off offset:64
	global_store_dwordx4 v[32:33], v[28:31], off
	global_store_dwordx4 v[32:33], v[20:23], off offset:64
	global_store_dwordx4 v[16:17], v[12:15], off
	global_store_dwordx4 v[16:17], v[4:7], off offset:64
	s_cbranch_vccnz .LBB0_1060
	s_barrier

; DI void final_norm(const Params& P, int G, int wave, int lane, float* dst) {
;     const int gw = blockIdx.x * 8 + wave, NGW = G * 8;
;     const bf16_t* h1b = (const bf16_t*)(P.ws + WS_H1B);
;     for (int m = MP + gw; m < MT; m += NGW) {
; __global__ void __launch_bounds__(512, 2) fwd_megakernel(Params P) {
;     ...
;     xcd_barrier(bar);
;     { FRESH_IDS; final_norm(P, G, wave, lane, P.out + O_Y); }
.LBB0_1102:
	s_cmp_lg_u32 s100, 0
	s_cbranch_scc1 .Lnb8_norm
	v_readlane_b32 s98, v255, 14
	s_cmpk_lt_u32 s98, 0x400
	s_cbranch_scc1 .LBB0_1157
	v_readlane_b32 s99, v255, 13
	s_sub_u32 s98, s98, 0x400
	s_add_u32 s64, s98, s99
	s_cmp_lg_u32 s99, 0
	s_cbranch_scc1 .Lnb8_wait
	s_mov_b64 exec, 1
	s_lshl_b32 s98, s33, 8
	s_add_u32 s98, s98, 0x54000
	v_mov_b32_e32 v0, s98
	v_mov_b32_e32 v1, 1
	v_mov_b32_e32 v3, 0x54800
	global_atomic_add v2, v0, v1, s[68:69] offset:128 sc0
	s_waitcnt vmcnt(0)
	v_cmp_ne_u32_e32 vcc, 0, v2
	s_cbranch_vccnz .Lnb8_poll
	s_mov_b32 s98, 0x10000
.Lnb8_pc:
	global_load_dword v2, v0, s[68:69] sc1
	s_waitcnt vmcnt(0)
	v_cmp_eq_u32_e32 vcc, 0x80, v2
	s_cbranch_vccnz .Lnb8_flush
	s_sleep 1
	s_sub_u32 s98, s98, 1
	s_cmp_lg_u32 s98, 0
	s_cbranch_scc1 .Lnb8_pc
.Lnb8_flush:
	buffer_wbl2 sc1
	s_waitcnt vmcnt(0)
	global_atomic_add v3, v1, s[68:69]
.Lnb8_poll:
	s_mov_b32 s98, 0x10000
.Lnb8_f:
	global_load_dword v2, v3, s[68:69] sc1
	s_waitcnt vmcnt(0)
	v_cmp_eq_u32_e32 vcc, 8, v2
	s_cbranch_vccnz .Lnb8_go
	s_sleep 1
	s_sub_u32 s98, s98, 1
	s_cmp_lg_u32 s98, 0
	s_cbranch_scc1 .Lnb8_f
.Lnb8_go:
	buffer_inv sc1
	s_mov_b64 exec, -1
.Lnb8_wait:
	s_barrier
	s_branch .Lnb8_p8

; DI float bflo(unsigned u) { return __uint_as_float(u << 16); }
; DI float bfhi(unsigned u) { return __uint_as_float(u & 0xffff0000u); }
; DI void final_norm(const Params& P, int G, int wave, int lane, float* dst) {
;     const int gw = blockIdx.x * 8 + wave, NGW = G * 8;
;     const bf16_t* h1b = (const bf16_t*)(P.ws + WS_H1B);
;     for (int m = MP + gw; m < MT; m += NGW) {
;         f32x4 v[4]; float s = 0.f;
; #pragma unroll
;         for (int j = 0; j < 4; ++j) { const u32x2 hb = *(const u32x2*)(h1b + (size_t)m * DM + 4 * lane + 256 * j); v[j] = (f32x4){bflo(hb.x), bfhi(hb.x), bflo(hb.y), bfhi(hb.y)}; }
;         const bf16_t* sl = (const bf16_t*)(P.ws + WS_SLAB) + (size_t)(m - MP) * DM + 4 * lane;
; #pragma unroll
;         for (int q = 0; q < NSPLIT_DN; ++q)
; #pragma unroll
;             for (int j = 0; j < 4; ++j) { const u32x2 sb = *(const u32x2*)(sl + (size_t)q * ((size_t)MS * DM) + 256 * j); v[j] += (f32x4){bflo(sb.x), bfhi(sb.x), bflo(sb.y), bfhi(sb.y)}; }
; #pragma unroll
;         for (int j = 0; j < 4; ++j) s += (v[j][0] * v[j][0] + v[j][1] * v[j][1]) + (v[j][2] * v[j][2] + v[j][3] * v[j][3]);
;         const float rs = rsqrtf(wave_sum(s) * (1.0f / DM) + EPS);
; #pragma unroll
;         for (int j = 0; j < 4; ++j) *(f32x4*)(dst + (size_t)m * DM + 4 * lane + 256 * j) = v[j] * rs * *(const f32x4*)(P.norm_f + 4 * lane + 256 * j);
.Lnb8_p8:
	v_mbcnt_lo_u32_b32 v2, -1, 0
	v_mbcnt_hi_u32_b32 v2, -1, v2
	v_lshlrev_b32_e32 v0, 3, v2
	v_lshlrev_b32_e32 v1, 4, v2
	v_lshlrev_b32_e32 v3, 2, v2
	global_load_dwordx4 v[160:163], v1, s[60:61]
	global_load_dwordx4 v[164:167], v1, s[60:61] offset:1024
	global_load_dwordx4 v[168:171], v1, s[60:61] offset:2048
	global_load_dwordx4 v[172:175], v1, s[60:61] offset:3072
